# hand-written SwiGLU GEMM epilogue (6 VALU per element, all ssq loads up front)
# speedup vs baseline: 1.0185x; 1.0185x over previous
.LBB0_537:
	s_andn2_b64 vcc, exec, s[10:11]
	s_cbranch_vccnz .LBB0_514
	s_mov_b64 s[10:11], -1
	s_cmp_eq_u32 s45, 1
	v_ashrrev_i32_e32 v163, 31, v162
	v_or_b32_e32 v134, 16, v162
	v_or_b32_e32 v130, 32, v162
	v_or_b32_e32 v132, 48, v162
	v_add_u32_e32 v128, 0x80, v162
	s_cbranch_scc1 .LBB0_540
	v_lshlrev_b64 v[164:165], 6, v[162:163]
	v_lshl_add_u64 v[164:165], v[156:157], 0, v[164:165]
	s_mov_b64 s[10:11], 0x2000
	global_load_dwordx4 v[190:193], v[164:165], off
	global_load_dwordx4 v[194:197], v[164:165], off offset:1024
	global_load_dwordx4 v[198:201], v[164:165], off offset:2048
	global_load_dwordx4 v[202:205], v[164:165], off offset:3072
	v_lshl_add_u64 v[166:167], v[164:165], 0, s[10:11]
	global_load_dwordx4 v[206:209], v[166:167], off
	global_load_dwordx4 v[210:213], v[166:167], off offset:1024
	global_load_dwordx4 v[214:217], v[166:167], off offset:2048
	global_load_dwordx4 v[218:221], v[166:167], off offset:3072
	v_mad_u64_u32 v[174:175], s[10:11], s28, v162, 0
	v_lshl_or_b32 v164, s25, 7, v186
	v_mov_b32_e32 v165, 0
	s_lshl_b64 s[78:79], s[28:29], 5
	s_lshl_b64 s[84:85], s[28:29], 8
	v_lshl_add_u64 v[174:175], v[174:175], 0, v[164:165]
	v_lshl_add_u64 v[174:175], v[174:175], 1, s[70:71]
	v_lshl_add_u64 v[166:167], v[174:175], 0, s[84:85]
	v_mov_b32_e32 v173, s56
	s_waitcnt vmcnt(0)
	v_add_f32_e32 v190, v190, v191
	v_add_f32_e32 v194, v194, v195
	v_add_f32_e32 v198, v198, v199
	v_add_f32_e32 v202, v202, v203
	v_add_f32_e32 v206, v206, v207
	v_add_f32_e32 v210, v210, v211
	v_add_f32_e32 v214, v214, v215
	v_add_f32_e32 v218, v218, v219
	v_add_f32_e32 v192, v192, v193
	v_add_f32_e32 v196, v196, v197
	v_add_f32_e32 v200, v200, v201
	v_add_f32_e32 v204, v204, v205
	v_add_f32_e32 v208, v208, v209
	v_add_f32_e32 v212, v212, v213
	v_add_f32_e32 v216, v216, v217
	v_add_f32_e32 v220, v220, v221
	v_add_f32_e32 v222, v190, v192
	v_add_f32_e32 v223, v194, v196
	v_add_f32_e32 v224, v198, v200
	v_add_f32_e32 v225, v202, v204
	v_add_f32_e32 v226, v206, v208
	v_add_f32_e32 v227, v210, v212
	v_add_f32_e32 v228, v214, v216
	v_add_f32_e32 v229, v218, v220
	v_mov_b32_e32 v135, v222
	v_mov_b32_e32 v136, v223
	v_mov_b32_e32 v137, v224
	v_mov_b32_e32 v138, v225
	v_mov_b32_e32 v139, v226
	v_mov_b32_e32 v140, v227
	v_mov_b32_e32 v141, v228
	v_mov_b32_e32 v142, v229
	s_nop 1
	v_permlane16_swap_b32_e32 v222, v135
	v_permlane16_swap_b32_e32 v223, v136
	v_permlane16_swap_b32_e32 v224, v137
	v_permlane16_swap_b32_e32 v225, v138
	v_permlane16_swap_b32_e32 v226, v139
	v_permlane16_swap_b32_e32 v227, v140
	v_permlane16_swap_b32_e32 v228, v141
	v_permlane16_swap_b32_e32 v229, v142
	v_add_f32_e32 v222, v222, v135
	v_add_f32_e32 v223, v223, v136
	v_add_f32_e32 v224, v224, v137
	v_add_f32_e32 v225, v225, v138
	v_add_f32_e32 v226, v226, v139
	v_add_f32_e32 v227, v227, v140
	v_add_f32_e32 v228, v228, v141
	v_add_f32_e32 v229, v229, v142
	v_mov_b32_e32 v135, v222
	v_mov_b32_e32 v136, v223
	v_mov_b32_e32 v137, v224
	v_mov_b32_e32 v138, v225
	v_mov_b32_e32 v139, v226
	v_mov_b32_e32 v140, v227
	v_mov_b32_e32 v141, v228
	v_mov_b32_e32 v142, v229
	s_nop 1
	v_permlane32_swap_b32_e32 v222, v135
	v_permlane32_swap_b32_e32 v223, v136
	v_permlane32_swap_b32_e32 v224, v137
	v_permlane32_swap_b32_e32 v225, v138
	v_permlane32_swap_b32_e32 v226, v139
	v_permlane32_swap_b32_e32 v227, v140
	v_permlane32_swap_b32_e32 v228, v141
	v_permlane32_swap_b32_e32 v229, v142
	v_add_f32_e32 v222, v222, v135
	v_add_f32_e32 v223, v223, v136
	v_add_f32_e32 v224, v224, v137
	v_add_f32_e32 v225, v225, v138
	v_add_f32_e32 v226, v226, v139
	v_add_f32_e32 v227, v227, v140
	v_add_f32_e32 v228, v228, v141
	v_add_f32_e32 v229, v229, v142
	v_fma_f32 v222, v222, s54, v173
	v_fma_f32 v223, v223, s54, v173
	v_fma_f32 v224, v224, s54, v173
	v_fma_f32 v225, v225, s54, v173
	v_fma_f32 v226, v226, s54, v173
	v_fma_f32 v227, v227, s54, v173
	v_fma_f32 v228, v228, s54, v173
	v_fma_f32 v229, v229, s54, v173
	v_rsq_f32_e32 v135, v222
	v_rsq_f32_e32 v136, v223
	v_rsq_f32_e32 v137, v224
	v_rsq_f32_e32 v138, v225
	v_rsq_f32_e32 v139, v226
	v_rsq_f32_e32 v140, v227
	v_rsq_f32_e32 v141, v228
	v_rsq_f32_e32 v142, v229
	s_nop 0
	v_mul_f32_e32 v135, 0xbfb8aa3b, v135
	v_mul_f32_e32 v136, 0xbfb8aa3b, v136
	v_mul_f32_e32 v137, 0xbfb8aa3b, v137
	v_mul_f32_e32 v138, 0xbfb8aa3b, v138
	v_mul_f32_e32 v139, 0xbfb8aa3b, v139
	v_mul_f32_e32 v140, 0xbfb8aa3b, v140
	v_mul_f32_e32 v141, 0xbfb8aa3b, v141
	v_mul_f32_e32 v142, 0xbfb8aa3b, v142
	v_mul_f32_e32 v190, v135, v124
	v_mul_f32_e32 v191, v135, v125
	v_mul_f32_e32 v192, v135, v126
	v_mul_f32_e32 v193, v135, v127
	v_mul_f32_e32 v194, v135, v116
	v_mul_f32_e32 v195, v135, v117
	v_mul_f32_e32 v196, v135, v118
	v_mul_f32_e32 v197, v135, v119
	v_exp_f32_e32 v190, v190
	v_exp_f32_e32 v191, v191
	v_exp_f32_e32 v192, v192
	v_exp_f32_e32 v193, v193
	v_exp_f32_e32 v194, v194
	v_exp_f32_e32 v195, v195
	v_exp_f32_e32 v196, v196
	v_exp_f32_e32 v197, v197
	v_mul_f32_e32 v198, v124, v108
	v_mul_f32_e32 v199, v125, v109
	v_mul_f32_e32 v200, v126, v110
	v_mul_f32_e32 v201, v127, v111
	v_mul_f32_e32 v202, v116, v100
	v_mul_f32_e32 v203, v117, v101
	v_mul_f32_e32 v204, v118, v102
	v_mul_f32_e32 v205, v119, v103
	v_fma_f32 v190, v190, v222, v222
	v_fma_f32 v191, v191, v222, v222
	v_fma_f32 v192, v192, v222, v222
	v_fma_f32 v193, v193, v222, v222
	v_fma_f32 v194, v194, v222, v222
	v_fma_f32 v195, v195, v222, v222
	v_fma_f32 v196, v196, v222, v222
	v_fma_f32 v197, v197, v222, v222
	v_rcp_f32_e32 v190, v190
	v_rcp_f32_e32 v191, v191
	v_rcp_f32_e32 v192, v192
	v_rcp_f32_e32 v193, v193
	v_rcp_f32_e32 v194, v194
	v_rcp_f32_e32 v195, v195
	v_rcp_f32_e32 v196, v196
	v_rcp_f32_e32 v197, v197
	s_nop 0
	v_mul_f32_e32 v198, v198, v190
	v_mul_f32_e32 v199, v199, v191
	v_mul_f32_e32 v200, v200, v192
	v_mul_f32_e32 v201, v201, v193
	v_mul_f32_e32 v202, v202, v194
	v_mul_f32_e32 v203, v203, v195
	v_mul_f32_e32 v204, v204, v196
	v_mul_f32_e32 v205, v205, v197
	v_cvt_pk_bf16_f32 v190, v198, v199
	v_cvt_pk_bf16_f32 v191, v200, v201
	v_cvt_pk_bf16_f32 v192, v202, v203
	v_cvt_pk_bf16_f32 v193, v204, v205
	global_store_dwordx4 v[174:175], v[190:193], off
	v_lshl_add_u64 v[174:175], v[174:175], 0, s[78:79]
	v_mul_f32_e32 v206, v136, v120
	v_mul_f32_e32 v207, v136, v121
	v_mul_f32_e32 v208, v136, v122
	v_mul_f32_e32 v209, v136, v123
	v_mul_f32_e32 v210, v136, v112
	v_mul_f32_e32 v211, v136, v113
	v_mul_f32_e32 v212, v136, v114
	v_mul_f32_e32 v213, v136, v115
	v_exp_f32_e32 v206, v206
	v_exp_f32_e32 v207, v207
	v_exp_f32_e32 v208, v208
	v_exp_f32_e32 v209, v209
	v_exp_f32_e32 v210, v210
	v_exp_f32_e32 v211, v211
	v_exp_f32_e32 v212, v212
	v_exp_f32_e32 v213, v213
	v_mul_f32_e32 v214, v120, v104
	v_mul_f32_e32 v215, v121, v105
	v_mul_f32_e32 v216, v122, v106
	v_mul_f32_e32 v217, v123, v107
	v_mul_f32_e32 v218, v112, v96
	v_mul_f32_e32 v219, v113, v97
	v_mul_f32_e32 v220, v114, v98
	v_mul_f32_e32 v221, v115, v99
	v_fma_f32 v206, v206, v223, v223
	v_fma_f32 v207, v207, v223, v223
	v_fma_f32 v208, v208, v223, v223
	v_fma_f32 v209, v209, v223, v223
	v_fma_f32 v210, v210, v223, v223
	v_fma_f32 v211, v211, v223, v223
	v_fma_f32 v212, v212, v223, v223
	v_fma_f32 v213, v213, v223, v223
	v_rcp_f32_e32 v206, v206
	v_rcp_f32_e32 v207, v207
	v_rcp_f32_e32 v208, v208
	v_rcp_f32_e32 v209, v209
	v_rcp_f32_e32 v210, v210
	v_rcp_f32_e32 v211, v211
	v_rcp_f32_e32 v212, v212
	v_rcp_f32_e32 v213, v213
	s_nop 0
	v_mul_f32_e32 v214, v214, v206
	v_mul_f32_e32 v215, v215, v207
	v_mul_f32_e32 v216, v216, v208
	v_mul_f32_e32 v217, v217, v209
	v_mul_f32_e32 v218, v218, v210
	v_mul_f32_e32 v219, v219, v211
	v_mul_f32_e32 v220, v220, v212
	v_mul_f32_e32 v221, v221, v213
	v_cvt_pk_bf16_f32 v206, v214, v215
	v_cvt_pk_bf16_f32 v207, v216, v217
	v_cvt_pk_bf16_f32 v208, v218, v219
	v_cvt_pk_bf16_f32 v209, v220, v221
	global_store_dwordx4 v[174:175], v[206:209], off
	v_lshl_add_u64 v[174:175], v[174:175], 0, s[78:79]
	v_mul_f32_e32 v190, v137, v92
	v_mul_f32_e32 v191, v137, v93
	v_mul_f32_e32 v192, v137, v94
	v_mul_f32_e32 v193, v137, v95
	v_mul_f32_e32 v194, v137, v84
	v_mul_f32_e32 v195, v137, v85
	v_mul_f32_e32 v196, v137, v86
	v_mul_f32_e32 v197, v137, v87
	v_exp_f32_e32 v190, v190
	v_exp_f32_e32 v191, v191
	v_exp_f32_e32 v192, v192
	v_exp_f32_e32 v193, v193
	v_exp_f32_e32 v194, v194
	v_exp_f32_e32 v195, v195
	v_exp_f32_e32 v196, v196
	v_exp_f32_e32 v197, v197
	v_mul_f32_e32 v198, v92, v76
	v_mul_f32_e32 v199, v93, v77
	v_mul_f32_e32 v200, v94, v78
	v_mul_f32_e32 v201, v95, v79
	v_mul_f32_e32 v202, v84, v68
	v_mul_f32_e32 v203, v85, v69
	v_mul_f32_e32 v204, v86, v70
	v_mul_f32_e32 v205, v87, v71
	v_fma_f32 v190, v190, v224, v224
	v_fma_f32 v191, v191, v224, v224
	v_fma_f32 v192, v192, v224, v224
	v_fma_f32 v193, v193, v224, v224
	v_fma_f32 v194, v194, v224, v224
	v_fma_f32 v195, v195, v224, v224
	v_fma_f32 v196, v196, v224, v224
	v_fma_f32 v197, v197, v224, v224
	v_rcp_f32_e32 v190, v190
	v_rcp_f32_e32 v191, v191
	v_rcp_f32_e32 v192, v192
	v_rcp_f32_e32 v193, v193
	v_rcp_f32_e32 v194, v194
	v_rcp_f32_e32 v195, v195
	v_rcp_f32_e32 v196, v196
	v_rcp_f32_e32 v197, v197
	s_nop 0
	v_mul_f32_e32 v198, v198, v190
	v_mul_f32_e32 v199, v199, v191
	v_mul_f32_e32 v200, v200, v192
	v_mul_f32_e32 v201, v201, v193
	v_mul_f32_e32 v202, v202, v194
	v_mul_f32_e32 v203, v203, v195
	v_mul_f32_e32 v204, v204, v196
	v_mul_f32_e32 v205, v205, v197
	v_cvt_pk_bf16_f32 v190, v198, v199
	v_cvt_pk_bf16_f32 v191, v200, v201
	v_cvt_pk_bf16_f32 v192, v202, v203
	v_cvt_pk_bf16_f32 v193, v204, v205
	global_store_dwordx4 v[174:175], v[190:193], off
	v_lshl_add_u64 v[174:175], v[174:175], 0, s[78:79]
	v_mul_f32_e32 v206, v138, v88
	v_mul_f32_e32 v207, v138, v89
	v_mul_f32_e32 v208, v138, v90
	v_mul_f32_e32 v209, v138, v91
	v_mul_f32_e32 v210, v138, v80
	v_mul_f32_e32 v211, v138, v81
	v_mul_f32_e32 v212, v138, v82
	v_mul_f32_e32 v213, v138, v83
	v_exp_f32_e32 v206, v206
	v_exp_f32_e32 v207, v207
	v_exp_f32_e32 v208, v208
	v_exp_f32_e32 v209, v209
	v_exp_f32_e32 v210, v210
	v_exp_f32_e32 v211, v211
	v_exp_f32_e32 v212, v212
	v_exp_f32_e32 v213, v213
	v_mul_f32_e32 v214, v88, v72
	v_mul_f32_e32 v215, v89, v73
	v_mul_f32_e32 v216, v90, v74
	v_mul_f32_e32 v217, v91, v75
	v_mul_f32_e32 v218, v80, v64
	v_mul_f32_e32 v219, v81, v65
	v_mul_f32_e32 v220, v82, v66
	v_mul_f32_e32 v221, v83, v67
	v_fma_f32 v206, v206, v225, v225
	v_fma_f32 v207, v207, v225, v225
	v_fma_f32 v208, v208, v225, v225
	v_fma_f32 v209, v209, v225, v225
	v_fma_f32 v210, v210, v225, v225
	v_fma_f32 v211, v211, v225, v225
	v_fma_f32 v212, v212, v225, v225
	v_fma_f32 v213, v213, v225, v225
	v_rcp_f32_e32 v206, v206
	v_rcp_f32_e32 v207, v207
	v_rcp_f32_e32 v208, v208
	v_rcp_f32_e32 v209, v209
	v_rcp_f32_e32 v210, v210
	v_rcp_f32_e32 v211, v211
	v_rcp_f32_e32 v212, v212
	v_rcp_f32_e32 v213, v213
	s_nop 0
	v_mul_f32_e32 v214, v214, v206
	v_mul_f32_e32 v215, v215, v207
	v_mul_f32_e32 v216, v216, v208
	v_mul_f32_e32 v217, v217, v209
	v_mul_f32_e32 v218, v218, v210
	v_mul_f32_e32 v219, v219, v211
	v_mul_f32_e32 v220, v220, v212
	v_mul_f32_e32 v221, v221, v213
	v_cvt_pk_bf16_f32 v206, v214, v215
	v_cvt_pk_bf16_f32 v207, v216, v217
	v_cvt_pk_bf16_f32 v208, v218, v219
	v_cvt_pk_bf16_f32 v209, v220, v221
	global_store_dwordx4 v[174:175], v[206:209], off
	v_mul_f32_e32 v190, v139, v60
	v_mul_f32_e32 v191, v139, v61
	v_mul_f32_e32 v192, v139, v62
	v_mul_f32_e32 v193, v139, v63
	v_mul_f32_e32 v194, v139, v56
	v_mul_f32_e32 v195, v139, v57
	v_mul_f32_e32 v196, v139, v58
	v_mul_f32_e32 v197, v139, v59
	v_exp_f32_e32 v190, v190
	v_exp_f32_e32 v191, v191
	v_exp_f32_e32 v192, v192
	v_exp_f32_e32 v193, v193
	v_exp_f32_e32 v194, v194
	v_exp_f32_e32 v195, v195
	v_exp_f32_e32 v196, v196
	v_exp_f32_e32 v197, v197
	v_mul_f32_e32 v198, v60, v44
	v_mul_f32_e32 v199, v61, v45
	v_mul_f32_e32 v200, v62, v46
	v_mul_f32_e32 v201, v63, v47
	v_mul_f32_e32 v202, v56, v36
	v_mul_f32_e32 v203, v57, v37
	v_mul_f32_e32 v204, v58, v38
	v_mul_f32_e32 v205, v59, v39
	v_fma_f32 v190, v190, v226, v226
	v_fma_f32 v191, v191, v226, v226
	v_fma_f32 v192, v192, v226, v226
	v_fma_f32 v193, v193, v226, v226
	v_fma_f32 v194, v194, v226, v226
	v_fma_f32 v195, v195, v226, v226
	v_fma_f32 v196, v196, v226, v226
	v_fma_f32 v197, v197, v226, v226
	v_rcp_f32_e32 v190, v190
	v_rcp_f32_e32 v191, v191
	v_rcp_f32_e32 v192, v192
	v_rcp_f32_e32 v193, v193
	v_rcp_f32_e32 v194, v194
	v_rcp_f32_e32 v195, v195
	v_rcp_f32_e32 v196, v196
	v_rcp_f32_e32 v197, v197
	s_nop 0
	v_mul_f32_e32 v198, v198, v190
	v_mul_f32_e32 v199, v199, v191
	v_mul_f32_e32 v200, v200, v192
	v_mul_f32_e32 v201, v201, v193
	v_mul_f32_e32 v202, v202, v194
	v_mul_f32_e32 v203, v203, v195
	v_mul_f32_e32 v204, v204, v196
	v_mul_f32_e32 v205, v205, v197
	v_cvt_pk_bf16_f32 v190, v198, v199
	v_cvt_pk_bf16_f32 v191, v200, v201
	v_cvt_pk_bf16_f32 v192, v202, v203
	v_cvt_pk_bf16_f32 v193, v204, v205
	global_store_dwordx4 v[166:167], v[190:193], off
	v_lshl_add_u64 v[166:167], v[166:167], 0, s[78:79]
	v_mul_f32_e32 v206, v140, v52
	v_mul_f32_e32 v207, v140, v53
	v_mul_f32_e32 v208, v140, v54
	v_mul_f32_e32 v209, v140, v55
	v_mul_f32_e32 v210, v140, v48
	v_mul_f32_e32 v211, v140, v49
	v_mul_f32_e32 v212, v140, v50
	v_mul_f32_e32 v213, v140, v51
	v_exp_f32_e32 v206, v206
	v_exp_f32_e32 v207, v207
	v_exp_f32_e32 v208, v208
	v_exp_f32_e32 v209, v209
	v_exp_f32_e32 v210, v210
	v_exp_f32_e32 v211, v211
	v_exp_f32_e32 v212, v212
	v_exp_f32_e32 v213, v213
	v_mul_f32_e32 v214, v52, v40
	v_mul_f32_e32 v215, v53, v41
	v_mul_f32_e32 v216, v54, v42
	v_mul_f32_e32 v217, v55, v43
	v_mul_f32_e32 v218, v48, v32
	v_mul_f32_e32 v219, v49, v33
	v_mul_f32_e32 v220, v50, v34
	v_mul_f32_e32 v221, v51, v35
	v_fma_f32 v206, v206, v227, v227
	v_fma_f32 v207, v207, v227, v227
	v_fma_f32 v208, v208, v227, v227
	v_fma_f32 v209, v209, v227, v227
	v_fma_f32 v210, v210, v227, v227
	v_fma_f32 v211, v211, v227, v227
	v_fma_f32 v212, v212, v227, v227
	v_fma_f32 v213, v213, v227, v227
	v_rcp_f32_e32 v206, v206
	v_rcp_f32_e32 v207, v207
	v_rcp_f32_e32 v208, v208
	v_rcp_f32_e32 v209, v209
	v_rcp_f32_e32 v210, v210
	v_rcp_f32_e32 v211, v211
	v_rcp_f32_e32 v212, v212
	v_rcp_f32_e32 v213, v213
	s_nop 0
	v_mul_f32_e32 v214, v214, v206
	v_mul_f32_e32 v215, v215, v207
	v_mul_f32_e32 v216, v216, v208
	v_mul_f32_e32 v217, v217, v209
	v_mul_f32_e32 v218, v218, v210
	v_mul_f32_e32 v219, v219, v211
	v_mul_f32_e32 v220, v220, v212
	v_mul_f32_e32 v221, v221, v213
	v_cvt_pk_bf16_f32 v206, v214, v215
	v_cvt_pk_bf16_f32 v207, v216, v217
	v_cvt_pk_bf16_f32 v208, v218, v219
	v_cvt_pk_bf16_f32 v209, v220, v221
	global_store_dwordx4 v[166:167], v[206:209], off
	v_lshl_add_u64 v[166:167], v[166:167], 0, s[78:79]
	v_mul_f32_e32 v190, v141, v28
	v_mul_f32_e32 v191, v141, v29
	v_mul_f32_e32 v192, v141, v30
	v_mul_f32_e32 v193, v141, v31
	v_mul_f32_e32 v194, v141, v20
	v_mul_f32_e32 v195, v141, v21
	v_mul_f32_e32 v196, v141, v22
	v_mul_f32_e32 v197, v141, v23
	v_exp_f32_e32 v190, v190
	v_exp_f32_e32 v191, v191
	v_exp_f32_e32 v192, v192
	v_exp_f32_e32 v193, v193
	v_exp_f32_e32 v194, v194
	v_exp_f32_e32 v195, v195
	v_exp_f32_e32 v196, v196
	v_exp_f32_e32 v197, v197
	v_mul_f32_e32 v198, v28, v12
	v_mul_f32_e32 v199, v29, v13
	v_mul_f32_e32 v200, v30, v14
	v_mul_f32_e32 v201, v31, v15
	v_mul_f32_e32 v202, v20, v4
	v_mul_f32_e32 v203, v21, v5
	v_mul_f32_e32 v204, v22, v6
	v_mul_f32_e32 v205, v23, v7
	v_fma_f32 v190, v190, v228, v228
	v_fma_f32 v191, v191, v228, v228
	v_fma_f32 v192, v192, v228, v228
	v_fma_f32 v193, v193, v228, v228
	v_fma_f32 v194, v194, v228, v228
	v_fma_f32 v195, v195, v228, v228
	v_fma_f32 v196, v196, v228, v228
	v_fma_f32 v197, v197, v228, v228
	v_rcp_f32_e32 v190, v190
	v_rcp_f32_e32 v191, v191
	v_rcp_f32_e32 v192, v192
	v_rcp_f32_e32 v193, v193
	v_rcp_f32_e32 v194, v194
	v_rcp_f32_e32 v195, v195
	v_rcp_f32_e32 v196, v196
	v_rcp_f32_e32 v197, v197
	s_nop 0
	v_mul_f32_e32 v198, v198, v190
	v_mul_f32_e32 v199, v199, v191
	v_mul_f32_e32 v200, v200, v192
	v_mul_f32_e32 v201, v201, v193
	v_mul_f32_e32 v202, v202, v194
	v_mul_f32_e32 v203, v203, v195
	v_mul_f32_e32 v204, v204, v196
	v_mul_f32_e32 v205, v205, v197
	v_cvt_pk_bf16_f32 v190, v198, v199
	v_cvt_pk_bf16_f32 v191, v200, v201
	v_cvt_pk_bf16_f32 v192, v202, v203
	v_cvt_pk_bf16_f32 v193, v204, v205
	global_store_dwordx4 v[166:167], v[190:193], off
	v_lshl_add_u64 v[166:167], v[166:167], 0, s[78:79]
	v_mul_f32_e32 v206, v142, v24
	v_mul_f32_e32 v207, v142, v25
	v_mul_f32_e32 v208, v142, v26
	v_mul_f32_e32 v209, v142, v27
	v_mul_f32_e32 v210, v142, v16
	v_mul_f32_e32 v211, v142, v17
	v_mul_f32_e32 v212, v142, v18
	v_mul_f32_e32 v213, v142, v19
	v_exp_f32_e32 v206, v206
	v_exp_f32_e32 v207, v207
	v_exp_f32_e32 v208, v208
	v_exp_f32_e32 v209, v209
	v_exp_f32_e32 v210, v210
	v_exp_f32_e32 v211, v211
	v_exp_f32_e32 v212, v212
	v_exp_f32_e32 v213, v213
	v_mul_f32_e32 v214, v24, v8
	v_mul_f32_e32 v215, v25, v9
	v_mul_f32_e32 v216, v26, v10
	v_mul_f32_e32 v217, v27, v11
	v_mul_f32_e32 v218, v16, v0
	v_mul_f32_e32 v219, v17, v1
	v_mul_f32_e32 v220, v18, v2
	v_mul_f32_e32 v221, v19, v3
	v_fma_f32 v206, v206, v229, v229
	v_fma_f32 v207, v207, v229, v229
	v_fma_f32 v208, v208, v229, v229
	v_fma_f32 v209, v209, v229, v229
	v_fma_f32 v210, v210, v229, v229
	v_fma_f32 v211, v211, v229, v229
	v_fma_f32 v212, v212, v229, v229
	v_fma_f32 v213, v213, v229, v229
	v_rcp_f32_e32 v206, v206
	v_rcp_f32_e32 v207, v207
	v_rcp_f32_e32 v208, v208
	v_rcp_f32_e32 v209, v209
	v_rcp_f32_e32 v210, v210
	v_rcp_f32_e32 v211, v211
	v_rcp_f32_e32 v212, v212
	v_rcp_f32_e32 v213, v213
	s_nop 0
	v_mul_f32_e32 v214, v214, v206
	v_mul_f32_e32 v215, v215, v207
	v_mul_f32_e32 v216, v216, v208
	v_mul_f32_e32 v217, v217, v209
	v_mul_f32_e32 v218, v218, v210
	v_mul_f32_e32 v219, v219, v211
	v_mul_f32_e32 v220, v220, v212
	v_mul_f32_e32 v221, v221, v213
	v_cvt_pk_bf16_f32 v206, v214, v215
	v_cvt_pk_bf16_f32 v207, v216, v217
	v_cvt_pk_bf16_f32 v208, v218, v219
	v_cvt_pk_bf16_f32 v209, v220, v221
	global_store_dwordx4 v[166:167], v[206:209], off
	s_branch .LBB0_514
